# mapping check with one barrier (per-class XCC census); norm P1 remapped and P1|P2 barrier XCD-local as well
# speedup vs baseline: 1.0190x; 1.0034x over previous
; __device__ __forceinline__ int lane_now() { int l; asm volatile("v_mbcnt_lo_u32_b32 %0, -1, 0\n\tv_mbcnt_hi_u32_b32 %0, -1, %0" : "=v"(l)); return l; }
; #define LAS __attribute__((address_space(3)))
; __device__ __forceinline__ unsigned xb_add(unsigned* p, unsigned v) { return __hip_atomic_fetch_add(p, v, __ATOMIC_RELAXED, __HIP_MEMORY_SCOPE_AGENT); }
; __device__ __forceinline__ unsigned xb_xcc_id() { return (unsigned)__builtin_amdgcn_s_getreg((3 << 11) | 20) & 0xFu; }
; __device__ __forceinline__ XcdBarrier xcd_barrier_post(unsigned* bar, volatile LAS unsigned* st, unsigned w0) {
;     XcdBarrier b; b.w0 = w0; b.bar = bar; b.x = xb_xcc_id(); b.st = st;
;     if (w0 && lane_now() == 0) (void)xb_add(&bar[XB_XCNT(b.x)], 1u);
;     return b;
; }
; __global__ void __launch_bounds__(512, 2) mega_fwd(Params p) {
;     ...
;     { const int t0_ = tid; if (t0_ < 2) *(LAS unsigned*)(lds + LDS_BYTES - 64 + 4 * t0_) = 0u; }
;     __syncthreads();
;     const XcdBarrier xbar = xcd_barrier_post((unsigned*)(ws + WS_BAR), (volatile LAS unsigned*)(lds + LDS_BYTES - 64), wave == 0 ? 1u : 0u);
_Z8mega_fwd6Params:
	s_load_dwordx8 s[88:95], s[0:1], 0xe0
	s_load_dwordx8 s[12:19], s[0:1], 0xc0
	v_writelane_b32 v244, s2, 0
	s_load_dword s2, s[0:1], 0x100
	v_and_b32_e32 v1, 0x3ff, v0
	s_add_u32 s6, s0, 0xf8
	s_addc_u32 s7, s1, 0
	v_mbcnt_lo_u32_b32 v2, -1, 0
	v_mbcnt_hi_u32_b32 v2, -1, v2
	s_waitcnt lgkmcnt(0)
	v_writelane_b32 v244, s2, 1
	v_readfirstlane_b32 s2, v1
	s_and_b32 s86, s2, 0xffffffc0
	v_add_u32_e32 v2, s86, v2
	v_cmp_gt_i32_e32 vcc, 2, v2
	v_writelane_b32 v244, s2, 2
	s_and_saveexec_b64 s[2:3], vcc
	v_lshl_add_u32 v2, v2, 2, 0
	v_add_u32_e32 v2, 0x23fc0, v2
	v_mov_b32_e32 v3, 0
	ds_write_b32 v2, v3
	s_or_b64 exec, exec, s[2:3]
	s_add_u32 s2, s92, 0xc0000
	s_addc_u32 s3, s93, 0
	v_writelane_b32 v244, s2, 3
	s_waitcnt lgkmcnt(0)
	s_barrier
	v_writelane_b32 v244, s3, 4
	s_nop 0
	v_readlane_b32 s4, v244, 2
	s_cmp_lt_u32 s4, 64
	s_getreg_b32 s87, hwreg(HW_REG_XCC_ID, 0, 4)
	s_cselect_b64 s[2:3], -1, 0
	s_and_b32 s5, s87, 15
	s_cmp_gt_u32 s4, 63
	v_writelane_b32 v244, s5, 5
	s_cbranch_scc1 .LBB0_7
	v_mbcnt_lo_u32_b32 v2, -1, 0
	v_mbcnt_hi_u32_b32 v2, -1, v2
	s_nop 0
	v_cmp_eq_u32_e32 vcc, 0, v2
	s_and_saveexec_b64 s[4:5], vcc
	s_cbranch_execz .LBB0_6
	s_mov_b64 s[8:9], exec
	v_mbcnt_lo_u32_b32 v2, s8, 0
	v_mbcnt_hi_u32_b32 v2, s9, v2
	v_cmp_eq_u32_e32 vcc, 0, v2
	s_and_b64 s[10:11], exec, vcc
	s_mov_b64 exec, s[10:11]
	s_cbranch_execz .LBB0_6
	v_readlane_b32 s10, v244, 5
	s_bcnt1_i32_b64 s8, s[8:9]
	s_lshl_b32 s10, s10, 8
	v_mov_b32_e32 v3, s8
	v_readlane_b32 s8, v244, 3
	v_mov_b32_e32 v2, s10
	v_readlane_b32 s9, v244, 4
	s_nop 4
	global_atomic_add v2, v3, s[8:9] offset:1024
	v_readlane_b32 s10, v244, 0
	s_and_b32 s10, s10, 7
	s_lshl_b32 s10, s10, 4
	v_readlane_b32 s11, v244, 5
	s_add_i32 s10, s10, s11
	s_lshl_b32 s10, s10, 2
	s_add_i32 s10, s10, 0x3c00
	v_mov_b32_e32 v2, s10
	v_mov_b32_e32 v3, 1
	global_atomic_add v2, v3, s[8:9]

; #define LAS __attribute__((address_space(3)))
; #define BAR_LDS() do { asm volatile("s_waitcnt lgkmcnt(0)" ::: "memory"); __builtin_amdgcn_s_barrier(); asm volatile("" ::: "memory"); } while (0)
; #define lane (lane_now())
; __device__ __forceinline__ void norm_phase(const float* src, const float* g, const float* mod, int ish, int isc, bf16_t* dst, LAS unsigned char* lds, int gw, int ngw, int wave, int lane) {
;     LAS float* GSl = (LAS float*)lds; LAS float* SHl = GSl + 4096;
;     for (int i = wave * 64 + lane; i < 4096; i += 512) { const int b = i >> 10, c = i & 1023; GSl[i] = g[c] * (1.f + mod[(size_t)b * NMOD + isc * 1024 + c]); SHl[i] = mod[(size_t)b * NMOD + ish * 1024 + c]; }
;     BAR_LDS();
; __global__ void __launch_bounds__(512, 2) mega_fwd(Params p) {
;     ...
;     grid.sync();
;     norm_phase(p.x, p.norm1_g, mod, 0, 1, XN, lds, gw, ngw, wave, lane);
;     xcd_barrier(xbar);
.Lgb0_141:
	s_mov_b64 exec, -1
	v_readlane_b32 s0, v245, 0
	v_readlane_b32 s1, v245, 1
	v_readlane_b32 s2, v245, 2
	v_readlane_b32 s3, v245, 3
	v_readlane_b32 s4, v245, 4
	v_readlane_b32 s5, v245, 5
	v_readlane_b32 s6, v245, 6
	v_readlane_b32 s7, v245, 7
	v_readlane_b32 s8, v245, 8
	v_readlane_b32 s9, v245, 9
	v_readlane_b32 s10, v245, 10
	v_readlane_b32 s11, v245, 11
	v_readlane_b32 s12, v245, 12
	v_readlane_b32 s13, v245, 13
	v_readlane_b32 s14, v245, 14
	v_readlane_b32 s15, v245, 15
	v_readlane_b32 s16, v245, 16
	v_readlane_b32 s17, v245, 17
	v_readlane_b32 s18, v245, 18
	v_readlane_b32 s19, v245, 19
	v_readlane_b32 s20, v245, 20
	v_readlane_b32 s21, v245, 21
	v_readlane_b32 s22, v245, 22
	v_readlane_b32 s23, v245, 23
	v_readlane_b32 s24, v245, 24
	v_readlane_b32 s25, v245, 25
	v_readlane_b32 s26, v245, 26
	v_readlane_b32 s27, v245, 27
	v_readlane_b32 s28, v245, 28
	v_readlane_b32 s29, v245, 29
	v_readlane_b32 s30, v245, 30
	v_readlane_b32 s31, v245, 31
	v_readlane_b32 s32, v245, 32
	v_readlane_b32 s33, v245, 33
	v_readlane_b32 s34, v245, 34
	v_readlane_b32 s35, v245, 35
	v_readlane_b32 s36, v245, 36
	v_readlane_b32 s37, v245, 37
	v_readlane_b32 s38, v245, 38
	v_readlane_b32 s39, v245, 39
	v_readlane_b32 s40, v245, 40
	v_readlane_b32 s41, v245, 41
	v_readlane_b32 s42, v245, 42
	v_readlane_b32 s43, v245, 43
	v_readlane_b32 s44, v245, 44
	v_readlane_b32 s45, v245, 45
	v_readlane_b32 s46, v245, 46
	v_readlane_b32 s47, v245, 47
	v_readlane_b32 s48, v245, 48
	v_readlane_b32 s49, v245, 49
	v_readlane_b32 s50, v245, 50
	v_readlane_b32 s51, v245, 51
	v_readlane_b32 s52, v245, 52
	v_readlane_b32 s53, v245, 53
	v_readlane_b32 s54, v245, 54
	v_readlane_b32 s55, v245, 55
	v_readlane_b32 s56, v245, 56
	v_readlane_b32 s57, v245, 57
	v_readlane_b32 s58, v245, 58
	v_readlane_b32 s59, v245, 59
	v_readlane_b32 s60, v245, 60
	v_readlane_b32 s61, v245, 61
	v_readlane_b32 s62, v245, 62
	v_readlane_b32 s63, v245, 63
	v_readlane_b32 s64, v246, 0
	v_readlane_b32 s65, v246, 1
	v_readlane_b32 s66, v246, 2
	v_readlane_b32 s67, v246, 3
	v_readlane_b32 s68, v246, 4
	v_readlane_b32 s69, v246, 5
	v_readlane_b32 s70, v246, 6
	v_readlane_b32 s71, v246, 7
	v_readlane_b32 s72, v246, 8
	v_readlane_b32 s73, v246, 9
	v_readlane_b32 s74, v246, 10
	v_readlane_b32 s75, v246, 11
	v_readlane_b32 s76, v246, 12
	v_readlane_b32 s77, v246, 13
	v_readlane_b32 s78, v246, 14
	v_readlane_b32 s79, v246, 15
	v_readlane_b32 s80, v246, 16
	v_readlane_b32 s81, v246, 17
	v_readlane_b32 s82, v246, 18
	v_readlane_b32 s83, v246, 19
	v_readlane_b32 s84, v246, 20
	v_readlane_b32 s85, v246, 21
	v_readlane_b32 s86, v246, 22
	v_readlane_b32 s87, v246, 23
	v_readlane_b32 s88, v246, 24
	v_readlane_b32 s89, v246, 25
	v_readlane_b32 s90, v246, 26
	v_readlane_b32 s91, v246, 27
	v_readlane_b32 s92, v246, 28
	v_readlane_b32 s93, v246, 29
	v_readlane_b32 s94, v246, 30
	v_readlane_b32 s95, v246, 31
	v_readlane_b32 s96, v246, 32
	v_readlane_b32 s97, v246, 33
	v_readlane_b32 vcc_lo, v246, 34
	v_readlane_b32 vcc_hi, v246, 35
	s_nop 7
	s_barrier
	v_mbcnt_lo_u32_b32 v245, -1, 0
	v_mbcnt_hi_u32_b32 v245, -1, v245
	v_lshlrev_b32_e32 v245, 3, v245
	v_add_u32_e32 v245, 0xc3c00, v245
	global_load_dwordx2 v[246:247], v245, s[92:93] sc1
	s_waitcnt vmcnt(0)
	v_add_u32_e32 v245, -32, v246
	v_mul_lo_u32 v246, v246, v245
	v_add_u32_e32 v245, -32, v247
	v_mul_lo_u32 v247, v247, v245
	v_or_b32_e32 v245, v246, v247
	v_cmp_eq_u32_e64 s[98:99], 0, v245
	s_nop 3
	s_cmp_eq_u64 s[98:99], -1
	s_cselect_b32 s100, 1, 0
	s_cmp_eq_u32 s94, 0x100
	s_cselect_b32 s100, s100, 0
	v_writelane_b32 v244, s100, 61
	v_mbcnt_lo_u32_b32 v0, -1, 0
	v_mbcnt_hi_u32_b32 v0, -1, v0
	s_movk_i32 s0, 0x1000
	v_add_u32_e32 v2, s86, v0
	v_cmp_gt_i32_e32 vcc, s0, v2
	s_and_saveexec_b64 s[6:7], vcc
	s_cbranch_execz .LBB0_84
	v_max_i32_e32 v1, 0xe00, v2
	v_sub_u32_e32 v1, v1, v2
	v_add_u32_e32 v3, 0x1ff, v1
	s_movk_i32 s0, 0xa00
	v_cmp_gt_u32_e64 s[10:11], s0, v3
	s_movk_i32 s0, 0x9ff
	v_cmp_lt_u32_e32 vcc, s0, v3
	s_and_saveexec_b64 s[16:17], vcc
	s_cbranch_execz .LBB0_81
	v_readlane_b32 s0, v244, 2
	v_lshrrev_b32_e32 v1, 9, v3
	s_and_b32 s0, s0, 0x3c0
	v_add_u16_e32 v4, s0, v0
	v_and_b32_e32 v5, 0x3ff, v1
	v_lshlrev_b16_e32 v6, 9, v1
	s_mov_b32 s4, 0x80000
	v_and_b32_e32 v4, 0x3ff, v4
	v_and_b32_e32 v6, 0x200, v6
	v_cmp_gt_u16_e32 vcc, 2, v5
	v_cmp_gt_u32_e64 s[4:5], s4, v3
	v_cmp_le_u16_e64 s[0:1], v6, v4
	s_and_b64 s[4:5], vcc, s[4:5]
	s_and_b64 s[20:21], s[4:5], s[0:1]
	s_mov_b64 s[4:5], -1
	s_and_saveexec_b64 s[0:1], s[20:21]
	s_cbranch_execz .LBB0_80
	v_add_u32_e32 v3, 0x200, v2
	v_add_u32_e32 v8, -1, v1
	v_cmp_lt_u32_e32 vcc, 1, v8
	v_mov_b32_e32 v6, 0
	v_mov_b64_e32 v[4:5], v[2:3]
	s_and_saveexec_b64 s[4:5], vcc
	s_cbranch_execz .LBB0_77
	v_lshrrev_b32_e32 v4, 1, v8
	s_lshl_b32 s20, s83, 8
	v_add_u32_e32 v4, 1, v4
	s_add_i32 s20, s20, 0
	v_and_b32_e32 v9, -2, v4
	s_mov_b32 s22, 0
	v_lshl_add_u32 v10, v0, 2, s20
	s_mov_b64 s[20:21], 0
	v_mov_b32_e32 v7, 0
	s_movk_i32 s23, 0x1000
	v_mov_b64_e32 v[4:5], v[2:3]

; #define LAS __attribute__((address_space(3)))
; __device__ __forceinline__ unsigned pk2(float lo, float hi) { const f32x2c v = {lo, hi}; const bf16x2c b = __builtin_convertvector(v, bf16x2c); return __builtin_bit_cast(unsigned, b); }
; #define lane (lane_now())
; __device__ __forceinline__ void norm_phase(const float* src, const float* g, const float* mod, int ish, int isc, bf16_t* dst, LAS unsigned char* lds, int gw, int ngw, int wave, int lane) {
;     ...
;     for (int m = gw; m < MTOK; m += ngw) {
;         const f32x4* xr = (const f32x4*)(src + (size_t)m * DM) + lane;
;         f32x4 v[4]; float s = 0.f;
; #pragma unroll
;         for (int j = 0; j < 4; ++j) { v[j] = xr[64 * j]; s += (v[j].x * v[j].x + v[j].y * v[j].y) + (v[j].z * v[j].z + v[j].w * v[j].w); }
;         s = wave_sum(s);
;         const float rstd = rsqrtf(s * (1.f / DM) + 1e-6f);
;         const int bo = (m >> 13) * 1024;
;         u32x2* o8 = (u32x2*)(dst + (size_t)m * DM) + lane;
; #pragma unroll
;         for (int j = 0; j < 4; ++j) { const int c = bo + 4 * lane + 256 * j;
;             const f32x4 gg = *(const LAS f32x4*)(GSl + c), h4 = *(const LAS f32x4*)(SHl + c);
;             const f32x4 o = v[j] * rstd * gg + h4;
;             u32x2 w; w.x = pk2(o.x, o.y); w.y = pk2(o.z, o.w); o8[64 * j] = w; }
;     }
.LBB0_84:
	s_or_b64 exec, exec, s[6:7]
	s_waitcnt lgkmcnt(0)
	s_barrier
	s_cmp_lt_i32 s78, 0x8000
	s_cselect_b64 s[0:1], -1, 0
	s_cmpk_gt_i32 s78, 0x7fff
	v_mbcnt_lo_u32_b32 v204, -1, 0
	s_cbranch_scc1 .LBB0_87
	s_mov_b32 s100, s78
	s_mov_b32 s101, s84
	s_mov_b32 s98, 0x8000
	v_readlane_b32 s99, v244, 61
	s_cmp_eq_u32 s99, 0
	s_cbranch_scc1 .Lxn_keep86
	s_lshr_b32 s99, s100, 3
	s_and_b32 s98, s99, 7
	s_lshl_b32 s98, s98, 12
	s_and_b32 s99, s99, 0xfffffff8
	s_and_b32 s78, s100, 7
	s_add_i32 s78, s78, s99
	s_add_i32 s78, s78, s98
	s_add_i32 s98, s98, 0x1000
	s_movk_i32 s84, 0x100
.Lxn_keep86:
	v_mbcnt_hi_u32_b32 v2, -1, v204
	v_and_b32_e32 v3, 64, v2
	v_add_u32_e32 v3, 64, v3
	v_xor_b32_e32 v4, 1, v2
	v_cmp_lt_i32_e32 vcc, v4, v3
	v_xor_b32_e32 v5, 2, v2
	v_xor_b32_e32 v6, 4, v2
	v_cndmask_b32_e32 v4, v2, v4, vcc
	v_cmp_lt_i32_e32 vcc, v5, v3
	v_xor_b32_e32 v7, 8, v2
	v_xor_b32_e32 v8, 16, v2
	v_cndmask_b32_e32 v5, v2, v5, vcc
	v_cmp_lt_i32_e32 vcc, v6, v3
	s_ashr_i32 s79, s78, 31
	v_xor_b32_e32 v9, 32, v2
	v_cndmask_b32_e32 v6, v2, v6, vcc
	v_cmp_lt_i32_e32 vcc, v7, v3
	s_lshl_b64 s[4:5], s[78:79], 11
	s_add_u32 s4, s92, s4
	v_cndmask_b32_e32 v7, v2, v7, vcc
	v_cmp_lt_i32_e32 vcc, v8, v3
	v_ashrrev_i32_e32 v1, 31, v0
	s_addc_u32 s5, s93, s5
	v_cndmask_b32_e32 v8, v2, v8, vcc
	v_cmp_lt_i32_e32 vcc, v9, v3
	s_ashr_i32 s85, s84, 31
	s_lshl_b64 s[6:7], s[78:79], 12
	v_cndmask_b32_e32 v2, v2, v9, vcc
	v_lshlrev_b32_e32 v9, 2, v2
	v_lshl_add_u64 v[2:3], v[0:1], 3, s[4:5]
	s_mov_b64 s[4:5], 0x2b00000
	v_lshl_add_u64 v[2:3], v[2:3], 0, s[4:5]
	s_lshl_b64 s[4:5], s[84:85], 11
	s_add_u32 s6, s36, s6
	s_addc_u32 s7, s37, s7
	v_lshlrev_b32_e32 v10, 2, v0
	v_lshl_add_u64 v[0:1], v[0:1], 4, s[6:7]
	s_mov_b64 s[6:7], 0xc00
	v_lshlrev_b32_e32 v4, 2, v4
	v_lshlrev_b32_e32 v5, 2, v5
	v_lshlrev_b32_e32 v6, 2, v6
	v_lshlrev_b32_e32 v7, 2, v7
	v_lshlrev_b32_e32 v8, 2, v8
	v_lshl_add_u64 v[0:1], v[0:1], 0, s[6:7]
	s_lshl_b64 s[6:7], s[84:85], 12
	v_mov_b32_e32 v11, 0x358637bd
	s_mov_b32 s10, 0x800000
	s_mov_b32 s11, s78
.LBB0_86:
	global_load_dwordx4 v[12:15], v[0:1], off offset:-3072
	global_load_dwordx4 v[16:19], v[0:1], off offset:-2048
	global_load_dwordx4 v[20:23], v[0:1], off offset:-1024
	global_load_dwordx4 v[24:27], v[0:1], off
	s_ashr_i32 s16, s11, 3
	s_and_b32 s16, s16, 0x3ffffc00
	v_add_u32_e32 v28, s16, v10
	v_lshl_add_u32 v56, v28, 2, 0
	ds_read_b128 v[28:31], v56
	ds_read_b128 v[32:35], v56 offset:1024
	ds_read_b128 v[36:39], v56 offset:16384
	ds_read_b128 v[40:43], v56 offset:17408
	ds_read_b128 v[44:47], v56 offset:2048
	ds_read_b128 v[48:51], v56 offset:3072
	ds_read_b128 v[52:55], v56 offset:18432
	ds_read_b128 v[56:59], v56 offset:19456
	s_add_i32 s11, s11, s84
	v_lshl_add_u64 v[0:1], v[0:1], 0, s[6:7]
	s_cmp_lt_i32 s11, s98
	s_waitcnt vmcnt(3)
	v_pk_mul_f32 v[60:61], v[14:15], v[14:15]
	v_pk_mul_f32 v[62:63], v[12:13], v[12:13]
	s_waitcnt vmcnt(2)
	v_pk_mul_f32 v[64:65], v[18:19], v[18:19]
	v_pk_mul_f32 v[66:67], v[16:17], v[16:17]
	v_pk_mov_b32 v[72:73], v[62:63], v[60:61] op_sel:[1,0]
	v_mov_b32_e32 v63, v61
	v_pk_mov_b32 v[60:61], v[66:67], v[64:65] op_sel:[1,0]
	v_mov_b32_e32 v67, v65
	s_waitcnt vmcnt(0)
	v_mul_f32_e32 v71, v24, v24
	v_mul_f32_e32 v68, v21, v21
	v_mul_f32_e32 v70, v23, v23
	v_pk_add_f32 v[62:63], v[72:73], v[62:63]
	v_pk_add_f32 v[60:61], v[60:61], v[66:67]
	v_mul_f32_e32 v74, v25, v25
	v_mul_f32_e32 v75, v26, v26
	v_mul_f32_e32 v76, v27, v27
	v_pk_fma_f32 v[64:65], v[20:21], v[20:21], v[68:69] op_sel_hi:[1,1,0]
	v_pk_fma_f32 v[68:69], v[22:23], v[22:23], v[70:71] op_sel_hi:[1,1,0]
	v_pk_add_f32 v[62:63], v[62:63], v[62:63] op_sel:[0,1] op_sel_hi:[1,0]
	v_pk_add_f32 v[60:61], v[60:61], v[60:61] op_sel:[0,1] op_sel_hi:[1,0]
	v_mov_b32_e32 v65, v75
	v_mov_b32_e32 v69, v76
	v_mov_b32_e32 v63, v71
	v_mov_b32_e32 v61, v74
	v_pk_add_f32 v[64:65], v[64:65], v[68:69]
	v_pk_add_f32 v[60:61], v[62:63], v[60:61]
	s_nop 0
	v_pk_add_f32 v[60:61], v[60:61], v[64:65]
	s_nop 0
	v_add_f32_e32 v60, v60, v61
	ds_bpermute_b32 v61, v4, v60
	s_waitcnt lgkmcnt(0)
	v_add_f32_e32 v60, v60, v61
	ds_bpermute_b32 v61, v5, v60
	s_waitcnt lgkmcnt(0)
	v_add_f32_e32 v60, v60, v61
	ds_bpermute_b32 v61, v6, v60
	s_waitcnt lgkmcnt(0)
	v_add_f32_e32 v60, v60, v61
	ds_bpermute_b32 v61, v7, v60
	s_waitcnt lgkmcnt(0)
	v_add_f32_e32 v60, v60, v61
	ds_bpermute_b32 v61, v8, v60
	s_waitcnt lgkmcnt(0)
	v_add_f32_e32 v60, v60, v61
	ds_bpermute_b32 v61, v9, v60
	s_waitcnt lgkmcnt(0)
	v_add_f32_e32 v60, v60, v61
	v_fmamk_f32 v60, v60, 0x3a800000, v11
	v_mul_f32_e32 v61, 0x4b800000, v60
	v_cmp_gt_f32_e32 vcc, s10, v60
	s_nop 1
	v_cndmask_b32_e32 v60, v60, v61, vcc
	v_rsq_f32_e32 v60, v60
	s_nop 0
	v_mul_f32_e32 v61, 0x45800000, v60
	v_cndmask_b32_e32 v60, v60, v61, vcc
	v_pk_mul_f32 v[12:13], v[12:13], v[60:61] op_sel_hi:[1,0]
	v_pk_mul_f32 v[14:15], v[14:15], v[60:61] op_sel_hi:[1,0]
	v_pk_mul_f32 v[16:17], v[16:17], v[60:61] op_sel_hi:[1,0]
	v_pk_mul_f32 v[18:19], v[18:19], v[60:61] op_sel_hi:[1,0]
	v_pk_mul_f32 v[20:21], v[20:21], v[60:61] op_sel_hi:[1,0]
	v_pk_mul_f32 v[22:23], v[22:23], v[60:61] op_sel_hi:[1,0]
	v_pk_mul_f32 v[24:25], v[24:25], v[60:61] op_sel_hi:[1,0]
	v_pk_mul_f32 v[26:27], v[26:27], v[60:61] op_sel_hi:[1,0]
	v_pk_fma_f32 v[14:15], v[30:31], v[14:15], v[38:39]
	v_pk_fma_f32 v[12:13], v[28:29], v[12:13], v[36:37]
	v_pk_fma_f32 v[18:19], v[34:35], v[18:19], v[42:43]
	v_pk_fma_f32 v[16:17], v[32:33], v[16:17], v[40:41]
	v_pk_fma_f32 v[22:23], v[46:47], v[22:23], v[54:55]
	v_pk_fma_f32 v[20:21], v[44:45], v[20:21], v[52:53]
	v_pk_fma_f32 v[26:27], v[50:51], v[26:27], v[58:59]
	v_pk_fma_f32 v[24:25], v[48:49], v[24:25], v[56:57]
	v_cvt_pk_bf16_f32 v12, v12, v13
	v_cvt_pk_bf16_f32 v13, v14, v15
	v_cvt_pk_bf16_f32 v14, v16, v17
	v_cvt_pk_bf16_f32 v15, v18, v19
	v_cvt_pk_bf16_f32 v16, v20, v21
	v_cvt_pk_bf16_f32 v17, v22, v23
	v_cvt_pk_bf16_f32 v18, v24, v25
	v_cvt_pk_bf16_f32 v19, v26, v27
	global_store_dwordx2 v[2:3], v[12:13], off
	global_store_dwordx2 v[2:3], v[14:15], off offset:512
	global_store_dwordx2 v[2:3], v[16:17], off offset:1024
	global_store_dwordx2 v[2:3], v[18:19], off offset:1536
	v_lshl_add_u64 v[2:3], v[2:3], 0, s[4:5]
	s_cbranch_scc1 .LBB0_86
	s_mov_b32 s78, s100
	s_mov_b32 s84, s101

; __device__ __forceinline__ int lane_now() { int l; asm volatile("v_mbcnt_lo_u32_b32 %0, -1, 0\n\tv_mbcnt_hi_u32_b32 %0, -1, %0" : "=v"(l)); return l; }
; __device__ __forceinline__ unsigned xb_ld(unsigned* p)              { return __hip_atomic_load(p, __ATOMIC_RELAXED, __HIP_MEMORY_SCOPE_AGENT); }
; __device__ __forceinline__ unsigned xb_add(unsigned* p, unsigned v) { return __hip_atomic_fetch_add(p, v, __ATOMIC_RELAXED, __HIP_MEMORY_SCOPE_AGENT); }
; #define XB_SPIN(cond, bar) do { unsigned _sp = 0; while (cond) { __builtin_amdgcn_s_sleep(1); \
;     if ((++_sp & 255u) == 0u) { if (xb_ld(&(bar)[XB_TMO])) break; if (_sp > XB_SPIN_CAP) { atomicAdd(&(bar)[XB_TMO], 1u); break; } } } } while (0)
; __device__ __forceinline__ void xcd_barrier(const XcdBarrier& b) {
;     asm volatile("s_waitcnt vmcnt(0)" ::: "memory");
;     __syncthreads();
;     if (b.w0 && lane_now() == 0) {
;         unsigned* bar = b.bar;
;         __builtin_amdgcn_s_waitcnt(0);
;         unsigned nloc = b.st[0], nx = b.st[1];
;         if (nloc == 0u) { xcd_barrier_complete(bar, b.x, nloc, nx); b.st[0] = nloc; b.st[1] = nx; }
;         const unsigned old = xb_add(&bar[XB_XSUB(b.x)], 1u);
;         const unsigned gen = old / nloc;
;         if (old + 1u == (gen + 1u) * nloc) {
;             __builtin_amdgcn_fence(__ATOMIC_RELEASE, "agent");
;             asm volatile("s_waitcnt vmcnt(0)" ::: "memory");
;             const unsigned og = xb_add(&bar[XB_TOP], 1u);
;             const unsigned tg = og / nx;
;             if (og + 1u == (tg + 1u) * nx) xb_add(&bar[XB_TOPGEN], 1u);
;             else XB_SPIN(xb_ld(&bar[XB_TOPGEN]) == tg, bar);
;             __builtin_amdgcn_fence(__ATOMIC_ACQUIRE, "agent");
;             xb_add(&bar[XB_XGEN(b.x)], 1u);
.LBB0_120:
	s_andn2_saveexec_b64 s[6:7], s[6:7]
	s_cbranch_execz .LBB0_140
	s_mov_b64 s[6:7], exec
	v_readlane_b32 s100, v244, 61
	s_cmp_lg_u32 s100, 0
	s_cbranch_scc1 .LBB0_137
	buffer_wbl2 sc1
	s_waitcnt lgkmcnt(0)
	s_waitcnt vmcnt(0)
	v_mbcnt_lo_u32_b32 v1, s6, 0
	v_mbcnt_hi_u32_b32 v1, s7, v1
	v_cmp_eq_u32_e32 vcc, 0, v1
	s_and_saveexec_b64 s[10:11], vcc
	s_cbranch_execz .LBB0_123
	s_bcnt1_i32_b64 s6, s[6:7]
	v_mov_b32_e32 v2, 0xc3000
	v_mov_b32_e32 v3, s6
	global_atomic_add v2, v2, v3, s[92:93] offset:1024 sc0
